# v058 + grid-barrier leader poll reads its 16 arrival counters with all loads in flight and sums after one wait (7 sites)
# speedup vs baseline: 1.0035x; 1.0035x over previous
; __device__ __forceinline__ unsigned xb_ld(unsigned* p)              { return __hip_atomic_load(p, __ATOMIC_RELAXED, __HIP_MEMORY_SCOPE_AGENT); }
; __device__ __forceinline__ void xcd_barrier_complete(unsigned* bar, unsigned x, unsigned& nloc, unsigned& nx) {
;     ...
;     for (;;) {
;         sum = 0u; cnt = 0u; mine = 0u;
; #pragma unroll
;         for (unsigned j = 0; j < 16; ++j) { const unsigned c = xb_ld(&bar[XB_XCNT(j)]); sum += c; cnt += (c > 0u) ? 1u : 0u; mine = (j == x) ? c : mine; }
;         if (sum == G) break;
;         __builtin_amdgcn_s_sleep(1);
;         if ((++sp & 255u) == 0u) { if (xb_ld(&bar[XB_TMO])) break; if (sp > XB_SPIN_CAP) { atomicAdd(&bar[XB_TMO], 1u); break; } }
;     }
.LBB0_154:
	v_readlane_b32 s6, v241, 9
	v_readlane_b32 s7, v241, 10
	global_load_dword v3, v155, s[96:97] sc1
	global_load_dword v0, v155, s[74:75] sc1
	global_load_dword v1, v155, s[52:53] sc1
	global_load_dword v2, v155, s[50:51] sc1
	s_mov_b64 s[8:9], -1
	global_load_dword v4, v155, s[6:7] sc1
	v_readlane_b32 s6, v241, 11
	v_readlane_b32 s7, v241, 12
	s_nop 0
	s_nop 0
	s_nop 2
	global_load_dword v5, v155, s[6:7] sc1
	v_readlane_b32 s6, v241, 13
	v_readlane_b32 s7, v241, 14
	s_nop 0
	s_nop 0
	s_nop 0
	s_nop 0
	s_nop 0
	s_nop 0
	s_nop 0
	s_nop 0
	global_load_dword v6, v155, s[6:7] sc1
	v_readlane_b32 s6, v241, 15
	v_readlane_b32 s7, v241, 16
	s_nop 0
	s_nop 0
	s_nop 2
	global_load_dword v7, v155, s[6:7] sc1
	v_readlane_b32 s6, v241, 17
	v_readlane_b32 s7, v241, 18
	s_nop 0
	s_nop 0
	s_nop 2
	global_load_dword v8, v155, s[6:7] sc1
	v_readlane_b32 s6, v241, 19
	v_readlane_b32 s7, v241, 20
	s_nop 0
	s_nop 0
	s_nop 2
	global_load_dword v9, v155, s[6:7] sc1
	v_readlane_b32 s6, v241, 21
	v_readlane_b32 s7, v241, 22
	s_nop 0
	s_nop 0
	s_nop 2
	global_load_dword v10, v155, s[6:7] sc1
	v_readlane_b32 s6, v241, 23
	v_readlane_b32 s7, v241, 24
	s_nop 0
	s_nop 0
	s_nop 2
	global_load_dword v11, v155, s[6:7] sc1
	v_readlane_b32 s6, v241, 25
	v_readlane_b32 s7, v241, 26
	s_nop 0
	s_nop 0
	s_nop 2
	global_load_dword v12, v155, s[6:7] sc1
	v_readlane_b32 s6, v241, 27
	v_readlane_b32 s7, v241, 28
	s_nop 0
	s_nop 0
	s_nop 2
	global_load_dword v13, v155, s[6:7] sc1
	v_readlane_b32 s6, v241, 29
	v_readlane_b32 s7, v241, 30
	s_nop 0
	s_nop 0
	s_nop 2
	global_load_dword v14, v155, s[6:7] sc1
	v_readlane_b32 s6, v241, 31
	v_readlane_b32 s7, v241, 32
	s_nop 0
	s_nop 0
	s_nop 2
	global_load_dword v15, v155, s[6:7] sc1
	s_mov_b64 s[6:7], -1
	s_nop 0
	s_nop 0
	s_waitcnt vmcnt(0)
	v_add_u32_e32 v16, v0, v3
	v_add_u32_e32 v16, v16, v1
	v_add_u32_e32 v16, v16, v2
	v_add_u32_e32 v16, v16, v4
	v_add_u32_e32 v16, v16, v5
	v_add_u32_e32 v16, v16, v6
	v_add_u32_e32 v16, v16, v7
	v_add_u32_e32 v16, v16, v8
	v_add_u32_e32 v16, v16, v9
	v_add_u32_e32 v16, v16, v10
	v_add_u32_e32 v16, v16, v11
	v_add_u32_e32 v16, v16, v12
	v_add_u32_e32 v16, v16, v13
	v_add_u32_e32 v16, v16, v14
	v_add_u32_e32 v16, v16, v15
	v_cmp_eq_u32_e32 vcc, s13, v16
	s_cbranch_vccnz .LBB0_153
	s_and_b32 s6, s14, 0xff
	s_cmp_eq_u32 s6, 0
	s_mov_b64 s[6:7], -1
	s_mov_b64 s[10:11], -1
	s_sleep 1
	s_cbranch_scc1 .LBB0_158
	s_and_b64 vcc, exec, s[10:11]
	s_cbranch_vccz .LBB0_153

; __device__ __forceinline__ unsigned xb_ld(unsigned* p)              { return __hip_atomic_load(p, __ATOMIC_RELAXED, __HIP_MEMORY_SCOPE_AGENT); }
; __device__ __forceinline__ void xcd_barrier_complete(unsigned* bar, unsigned x, unsigned& nloc, unsigned& nx) {
;     ...
;     for (;;) {
;         sum = 0u; cnt = 0u; mine = 0u;
; #pragma unroll
;         for (unsigned j = 0; j < 16; ++j) { const unsigned c = xb_ld(&bar[XB_XCNT(j)]); sum += c; cnt += (c > 0u) ? 1u : 0u; mine = (j == x) ? c : mine; }
;         if (sum == G) break;
;         __builtin_amdgcn_s_sleep(1);
;         if ((++sp & 255u) == 0u) { if (xb_ld(&bar[XB_TMO])) break; if (sp > XB_SPIN_CAP) { atomicAdd(&bar[XB_TMO], 1u); break; } }
;     }
.LBB0_678:
	v_readlane_b32 s8, v241, 9
	v_readlane_b32 s9, v241, 10
	global_load_dword v3, v155, s[96:97] sc1
	global_load_dword v0, v155, s[74:75] sc1
	global_load_dword v1, v155, s[52:53] sc1
	global_load_dword v2, v155, s[50:51] sc1
	s_mov_b64 s[10:11], -1
	global_load_dword v4, v155, s[8:9] sc1
	v_readlane_b32 s8, v241, 11
	v_readlane_b32 s9, v241, 12
	s_nop 0
	s_nop 0
	s_nop 2
	global_load_dword v5, v155, s[8:9] sc1
	v_readlane_b32 s8, v241, 13
	v_readlane_b32 s9, v241, 14
	s_nop 0
	s_nop 0
	s_nop 0
	s_nop 0
	s_nop 0
	s_nop 0
	s_nop 0
	s_nop 0
	global_load_dword v6, v155, s[8:9] sc1
	v_readlane_b32 s8, v241, 15
	v_readlane_b32 s9, v241, 16
	s_nop 0
	s_nop 0
	s_nop 2
	global_load_dword v7, v155, s[8:9] sc1
	v_readlane_b32 s8, v241, 17
	v_readlane_b32 s9, v241, 18
	s_nop 0
	s_nop 0
	s_nop 2
	global_load_dword v8, v155, s[8:9] sc1
	v_readlane_b32 s8, v241, 19
	v_readlane_b32 s9, v241, 20
	s_nop 0
	s_nop 0
	s_nop 2
	global_load_dword v9, v155, s[8:9] sc1
	v_readlane_b32 s8, v241, 21
	v_readlane_b32 s9, v241, 22
	s_nop 0
	s_nop 0
	s_nop 2
	global_load_dword v10, v155, s[8:9] sc1
	v_readlane_b32 s8, v241, 23
	v_readlane_b32 s9, v241, 24
	s_nop 0
	s_nop 0
	s_nop 2
	global_load_dword v11, v155, s[8:9] sc1
	v_readlane_b32 s8, v241, 25
	v_readlane_b32 s9, v241, 26
	s_nop 0
	s_nop 0
	s_nop 2
	global_load_dword v12, v155, s[8:9] sc1
	v_readlane_b32 s8, v241, 27
	v_readlane_b32 s9, v241, 28
	s_nop 0
	s_nop 0
	s_nop 2
	global_load_dword v13, v155, s[8:9] sc1
	v_readlane_b32 s8, v241, 29
	v_readlane_b32 s9, v241, 30
	s_nop 0
	s_nop 0
	s_nop 2
	global_load_dword v14, v155, s[8:9] sc1
	v_readlane_b32 s8, v241, 31
	v_readlane_b32 s9, v241, 32
	s_nop 0
	s_nop 0
	s_nop 2
	global_load_dword v15, v155, s[8:9] sc1
	s_mov_b64 s[8:9], -1
	s_nop 0
	s_nop 0
	s_waitcnt vmcnt(0)
	v_add_u32_e32 v16, v0, v3
	v_add_u32_e32 v16, v16, v1
	v_add_u32_e32 v16, v16, v2
	v_add_u32_e32 v16, v16, v4
	v_add_u32_e32 v16, v16, v5
	v_add_u32_e32 v16, v16, v6
	v_add_u32_e32 v16, v16, v7
	v_add_u32_e32 v16, v16, v8
	v_add_u32_e32 v16, v16, v9
	v_add_u32_e32 v16, v16, v10
	v_add_u32_e32 v16, v16, v11
	v_add_u32_e32 v16, v16, v12
	v_add_u32_e32 v16, v16, v13
	v_add_u32_e32 v16, v16, v14
	v_add_u32_e32 v16, v16, v15
	v_cmp_eq_u32_e32 vcc, s15, v16
	s_cbranch_vccnz .LBB0_677
	s_and_b32 s8, s16, 0xff
	s_cmp_eq_u32 s8, 0
	s_mov_b64 s[8:9], -1
	s_mov_b64 s[12:13], -1
	s_sleep 1
	s_cbranch_scc1 .LBB0_682
	s_and_b64 vcc, exec, s[12:13]
	s_cbranch_vccz .LBB0_677
